# FOX attention tile loop restructured as two-group ping-pong (QK segment / exp+PV segment, 2 barriers per tile, 4-slot LDS ring, cum via LDS-DMA)
# baseline (speedup 1.0000x reference)
.LBB0_875:
	s_cmp_gt_u32 s15, 0xff
	s_cselect_b32 s78, 1, 0
	v_mov_b32_e32 v241, 0
	s_mov_b32 s71, 0
	s_mov_b32 s46, s44
	s_mov_b32 s47, s44
	s_mov_b32 s72, 1
	s_and_b32 s7, s72, 1
	s_lshl_b32 s7, s7, 13
	s_and_b32 s50, s72, 2
	s_lshl_b32 s50, s50, 14
	s_add_i32 s7, s7, s50
	s_add_i32 s7, s7, s2
	s_lshl_b32 s50, s72, 6
	v_add_u32_e32 v240, s50, v128
	v_lshlrev_b64 v[242:243], 11, v[240:241]
	v_lshl_add_u64 v[242:243], s[88:89], 0, v[242:243]
	s_mov_b32 m0, s7
	v_add_u32_e32 v240, s50, v138
	global_load_lds_dwordx4 v[242:243], off
	v_lshlrev_b64 v[242:243], 11, v[240:241]
	v_lshl_add_u64 v[242:243], v[132:133], 0, v[242:243]
	s_add_i32 m0, s7, 0x4000
	s_nop 0
	global_load_lds_dwordx4 v[242:243], off
	s_and_b64 vcc, exec, s[86:87]
	s_cbranch_vccz .Lfx_noc_p
	s_and_b32 s7, s72, 3
	s_lshl_b32 s7, s7, 8
	s_add_i32 s7, s7, 0x10000
	s_lshl_b32 s50, s72, 8
	v_lshl_add_u64 v[242:243], v[130:131], 0, s[50:51]
	s_mov_b32 m0, s7
	s_nop 0
	global_load_lds_dword v[242:243], off
.Lfx_noc_p:
	s_waitcnt lgkmcnt(0)
	s_cmp_eq_u32 s78, 0
	s_cbranch_scc1 .Lfx_loop
	s_barrier
.Lfx_loop:
	s_barrier
	s_cmp_gt_i32 s71, s53
	s_cbranch_scc1 .Lfx_skip1
	s_and_b32 s72, s71, 3
	v_lshl_add_u32 v252, s72, 8, v139
	s_and_b32 s79, s71, 1
	s_lshl_b32 s79, s79, 13
	s_and_b32 s45, s71, 2
	s_lshl_b32 s45, s45, 14
	s_add_i32 s45, s45, s79
	ds_read_b128 v[80:83], v252
	ds_read_b128 v[84:87], v252 offset:32
	ds_read_b128 v[88:91], v252 offset:64
	ds_read_b128 v[92:95], v252 offset:96
	v_add3_u32 v253, s45, v140, v141
	ds_read_b128 v[96:99], v252 offset:128
	ds_read_b128 v[100:103], v252 offset:160
	ds_read_b128 v[104:107], v252 offset:192
	ds_read_b128 v[108:111], v252 offset:224
	v_add_u32_e32 v250, s45, v142
	ds_read_b128 v[146:149], v253
	ds_read_b128 v[150:153], v253 offset:512
	ds_read_b128 v[154:157], v253 offset:2048
	ds_read_b128 v[158:161], v253 offset:2560
	v_add3_u32 v250, v250, v129, v143
	ds_read_b128 v[162:165], v253 offset:4096
	ds_read_b128 v[166:169], v253 offset:4608
	ds_read_b128 v[180:183], v253 offset:6144
	ds_read_b128 v[184:187], v253 offset:6656
	s_mov_b32 s45, s44
	s_waitcnt lgkmcnt(8)
	v_sub_f32_e32 v80, v48, v80
	v_sub_f32_e32 v81, v48, v81
	v_sub_f32_e32 v82, v48, v82
	v_sub_f32_e32 v83, v48, v83
	v_sub_f32_e32 v84, v48, v84
	v_sub_f32_e32 v85, v48, v85
	v_sub_f32_e32 v86, v48, v86
	v_sub_f32_e32 v87, v48, v87
	v_sub_f32_e32 v88, v48, v88
	v_sub_f32_e32 v89, v48, v89
	v_sub_f32_e32 v90, v48, v90
	v_sub_f32_e32 v91, v48, v91
	v_sub_f32_e32 v92, v48, v92
	v_sub_f32_e32 v93, v48, v93
	v_sub_f32_e32 v94, v48, v94
	v_sub_f32_e32 v95, v48, v95
	ds_read_b64_tr_b16 v[188:189], v250 offset:16384
	ds_read_b64_tr_b16 v[190:191], v250 offset:16896
	ds_read_b64_tr_b16 v[192:193], v250 offset:17408
	ds_read_b64_tr_b16 v[194:195], v250 offset:17920
	v_sub_f32_e32 v96, v48, v96
	v_sub_f32_e32 v97, v48, v97
	v_sub_f32_e32 v98, v48, v98
	v_sub_f32_e32 v99, v48, v99
	v_sub_f32_e32 v100, v48, v100
	v_sub_f32_e32 v101, v48, v101
	v_sub_f32_e32 v102, v48, v102
	v_sub_f32_e32 v103, v48, v103
	v_sub_f32_e32 v104, v48, v104
	v_sub_f32_e32 v105, v48, v105
	v_sub_f32_e32 v106, v48, v106
	v_sub_f32_e32 v107, v48, v107
	v_sub_f32_e32 v108, v48, v108
	v_sub_f32_e32 v109, v48, v109
	v_sub_f32_e32 v110, v48, v110
	v_sub_f32_e32 v111, v48, v111
	ds_read_b64_tr_b16 v[196:197], v250 offset:18432
	ds_read_b64_tr_b16 v[198:199], v250 offset:18944
	ds_read_b64_tr_b16 v[200:201], v250 offset:19456
	s_waitcnt lgkmcnt(14)
	v_mfma_f32_32x32x16_bf16 v[80:95], v[146:149], v[112:115], v[80:95]
	s_waitcnt lgkmcnt(13)
	v_mfma_f32_32x32x16_bf16 v[96:111], v[150:153], v[112:115], v[96:111]
	ds_read_b64_tr_b16 v[202:203], v250 offset:19968
	s_waitcnt lgkmcnt(13)
	v_mfma_f32_32x32x16_bf16 v[80:95], v[154:157], v[116:119], v[80:95]
	s_waitcnt lgkmcnt(12)
	v_mfma_f32_32x32x16_bf16 v[96:111], v[158:161], v[116:119], v[96:111]
	ds_read_b64_tr_b16 v[204:205], v250 offset:20480
	ds_read_b64_tr_b16 v[206:207], v250 offset:20992
	s_waitcnt lgkmcnt(13)
	v_mfma_f32_32x32x16_bf16 v[80:95], v[162:165], v[120:123], v[80:95]
	s_waitcnt lgkmcnt(12)
	v_mfma_f32_32x32x16_bf16 v[96:111], v[166:169], v[120:123], v[96:111]
	ds_read_b64_tr_b16 v[208:209], v250 offset:21504
	ds_read_b64_tr_b16 v[210:211], v250 offset:22016
	s_waitcnt lgkmcnt(13)
	v_mfma_f32_32x32x16_bf16 v[80:95], v[180:183], v[124:127], v[80:95]
	s_waitcnt lgkmcnt(12)
	v_mfma_f32_32x32x16_bf16 v[96:111], v[184:187], v[124:127], v[96:111]
	ds_read_b64_tr_b16 v[212:213], v250 offset:22528
	ds_read_b64_tr_b16 v[214:215], v250 offset:23040
	ds_read_b64_tr_b16 v[216:217], v250 offset:23552
	ds_read_b64_tr_b16 v[218:219], v250 offset:24064
	v_mov_b32_e32 v236, s44
	v_mov_b32_e32 v237, s44
	v_mov_b32_e32 v238, s44
	v_mov_b32_e32 v239, s44
	s_cmp_le_i32 s60, s40
	s_cbranch_scc1 .LBB0_881
	v_cmp_gt_i32_e32 vcc, 0, v144
	v_cmp_gt_i32_e64 s[6:7], 1, v144
	s_and_b64 vcc, s[6:7], vcc
	s_nop 4
	v_cndmask_b32_e32 v80, v80, v235, vcc
	v_cmp_lt_i32_e32 vcc, 1, v144
	v_cmp_gt_i32_e64 s[36:37], 58, v144
	v_cmp_gt_i32_e64 s[38:39], 59, v144
	v_cndmask_b32_e32 v82, v235, v82, vcc
	v_cmp_lt_i32_e32 vcc, 2, v144
	v_cmp_gt_i32_e64 s[34:35], 57, v144
	s_and_b64 s[36:37], s[38:39], s[36:37]
	v_cndmask_b32_e32 v83, v235, v83, vcc
	v_cmp_lt_i32_e32 vcc, 7, v144
	v_cmp_gt_i32_e64 s[30:31], 56, v144
	s_and_b64 s[34:35], s[36:37], s[34:35]
	v_cndmask_b32_e32 v84, v235, v84, vcc
	v_cmp_lt_i32_e32 vcc, 8, v144
	v_cmp_gt_i32_e64 s[28:29], 51, v144
	s_and_b64 s[30:31], s[34:35], s[30:31]
	v_cndmask_b32_e32 v85, v235, v85, vcc
	v_cmp_lt_i32_e32 vcc, 9, v144
	v_cmp_gt_i32_e64 s[26:27], 50, v144
	s_and_b64 s[28:29], s[30:31], s[28:29]
	v_cndmask_b32_e32 v86, v235, v86, vcc
	v_cmp_lt_i32_e32 vcc, 10, v144
	v_cmp_gt_i32_e64 s[24:25], 49, v144
	s_and_b64 s[26:27], s[28:29], s[26:27]
	v_cndmask_b32_e32 v87, v235, v87, vcc
	v_cmp_lt_i32_e32 vcc, 15, v144
	v_cmp_gt_i32_e64 s[22:23], 48, v144
	s_and_b64 s[24:25], s[26:27], s[24:25]
	v_cndmask_b32_e32 v88, v235, v88, vcc
	v_cmp_lt_i32_e32 vcc, 16, v144
	v_cmp_gt_i32_e64 s[20:21], 43, v144
	s_and_b64 s[22:23], s[24:25], s[22:23]
	v_cndmask_b32_e32 v89, v235, v89, vcc
	v_cmp_lt_i32_e32 vcc, 17, v144
	v_cmp_gt_i32_e64 s[18:19], 42, v144
	s_and_b64 s[20:21], s[22:23], s[20:21]
	v_cndmask_b32_e32 v90, v235, v90, vcc
	v_cmp_lt_i32_e32 vcc, 18, v144
	v_cmp_gt_i32_e64 s[16:17], 41, v144
	s_and_b64 s[18:19], s[20:21], s[18:19]
	v_cndmask_b32_e32 v91, v235, v91, vcc
	v_cmp_lt_i32_e32 vcc, 23, v144
	v_cmp_gt_i32_e64 s[14:15], 40, v144
	s_and_b64 s[16:17], s[18:19], s[16:17]
	v_cndmask_b32_e32 v92, v235, v92, vcc
	v_cmp_lt_i32_e32 vcc, 24, v144
	v_cmp_gt_i32_e64 s[10:11], 35, v144
	s_and_b64 s[14:15], s[16:17], s[14:15]
	v_cndmask_b32_e32 v93, v235, v93, vcc
	v_cmp_lt_i32_e32 vcc, 25, v144
	v_cmp_gt_i32_e64 s[8:9], 34, v144
	s_and_b64 s[10:11], s[14:15], s[10:11]
	v_cndmask_b32_e64 v81, v81, v235, s[6:7]
	v_cndmask_b32_e32 v94, v235, v94, vcc
	v_cmp_lt_i32_e32 vcc, 26, v144
	v_cmp_gt_i32_e64 s[6:7], 33, v144
	s_and_b64 s[8:9], s[10:11], s[8:9]
	v_cndmask_b32_e32 v0, v235, v95, vcc
	v_cmp_gt_i32_e32 vcc, 32, v144
	s_and_b64 s[6:7], s[8:9], s[6:7]
	s_and_b64 vcc, s[6:7], vcc
	v_cndmask_b32_e64 v111, v111, v235, s[38:39]
	v_cndmask_b32_e64 v110, v110, v235, s[36:37]
	v_cndmask_b32_e64 v109, v109, v235, s[34:35]
	v_cndmask_b32_e64 v108, v108, v235, s[30:31]
	v_cndmask_b32_e64 v107, v107, v235, s[28:29]
	v_cndmask_b32_e64 v106, v106, v235, s[26:27]
	v_cndmask_b32_e64 v105, v105, v235, s[24:25]
	v_cndmask_b32_e64 v104, v104, v235, s[22:23]
	v_cndmask_b32_e64 v103, v103, v235, s[20:21]
	v_cndmask_b32_e64 v102, v102, v235, s[18:19]
	v_cndmask_b32_e64 v101, v101, v235, s[16:17]
	v_cndmask_b32_e64 v100, v100, v235, s[14:15]
	v_cndmask_b32_e64 v99, v99, v235, s[10:11]
	v_cndmask_b32_e64 v98, v98, v235, s[8:9]
	v_cndmask_b32_e64 v97, v97, v235, s[6:7]
	v_cndmask_b32_e32 v95, v95, v0, vcc
	v_cndmask_b32_e32 v96, v96, v235, vcc
.LBB0_881:
.Lfx_skip1:
	s_waitcnt vmcnt(0)
	s_barrier
	s_add_i32 s72, s71, 2
	s_cmp_ge_u32 s72, s41
	s_cbranch_scc1 .Lfx_noissue
	s_and_b32 s7, s72, 1
	s_lshl_b32 s7, s7, 13
	s_and_b32 s50, s72, 2
	s_lshl_b32 s50, s50, 14
	s_add_i32 s7, s7, s50
	s_add_i32 s7, s7, s2
	s_lshl_b32 s50, s72, 6
	v_add_u32_e32 v240, s50, v128
	v_lshlrev_b64 v[242:243], 11, v[240:241]
	v_lshl_add_u64 v[242:243], s[88:89], 0, v[242:243]
	s_mov_b32 m0, s7
	v_add_u32_e32 v240, s50, v138
	global_load_lds_dwordx4 v[242:243], off
	v_lshlrev_b64 v[242:243], 11, v[240:241]
	v_lshl_add_u64 v[242:243], v[132:133], 0, v[242:243]
	s_add_i32 m0, s7, 0x4000
	s_nop 0
	global_load_lds_dwordx4 v[242:243], off
	s_and_b64 vcc, exec, s[86:87]
	s_cbranch_vccz .Lfx_noc_l
	s_and_b32 s7, s72, 3
	s_lshl_b32 s7, s7, 8
	s_add_i32 s7, s7, 0x10000
	s_lshl_b32 s50, s72, 8
	v_lshl_add_u64 v[242:243], v[130:131], 0, s[50:51]
	s_mov_b32 m0, s7
	s_nop 0
	global_load_lds_dword v[242:243], off
.Lfx_noc_l:
.Lfx_noissue:
	s_cmp_gt_i32 s71, s53
	s_cbranch_scc1 .Lfx_skip2
	v_exp_f32_e32 v80, v80
	v_exp_f32_e32 v81, v81
	v_exp_f32_e32 v82, v82
	v_exp_f32_e32 v83, v83
	v_exp_f32_e32 v84, v84
	v_exp_f32_e32 v85, v85
	v_exp_f32_e32 v86, v86
	v_exp_f32_e32 v87, v87
	v_exp_f32_e32 v88, v88
	v_exp_f32_e32 v89, v89
	v_exp_f32_e32 v90, v90
	v_exp_f32_e32 v91, v91
	v_exp_f32_e32 v92, v92
	v_exp_f32_e32 v93, v93
	v_exp_f32_e32 v94, v94
	v_exp_f32_e32 v95, v95
	v_cvt_pk_bf16_f32 v2, v80, v81
	v_cvt_pk_bf16_f32 v3, v82, v83
	v_cvt_pk_bf16_f32 v4, v84, v85
	v_cvt_pk_bf16_f32 v5, v86, v87
	v_cvt_pk_bf16_f32 v6, v88, v89
	v_cvt_pk_bf16_f32 v7, v90, v91
	v_cvt_pk_bf16_f32 v8, v92, v93
	v_cvt_pk_bf16_f32 v9, v94, v95
	s_waitcnt lgkmcnt(0)
	v_mfma_f32_32x32x16_bf16 v[32:47], v[2:5], v[188:191], v[32:47]
	v_exp_f32_e32 v96, v96
	v_exp_f32_e32 v97, v97
	v_exp_f32_e32 v98, v98
	v_mfma_f32_32x32x16_bf16 v[32:47], v[6:9], v[192:195], v[32:47]
	v_exp_f32_e32 v99, v99
	v_exp_f32_e32 v100, v100
	v_exp_f32_e32 v101, v101
	v_mfma_f32_32x32x16_bf16 v[16:31], v[2:5], v[204:207], v[16:31]
	v_exp_f32_e32 v102, v102
	v_exp_f32_e32 v103, v103
	v_exp_f32_e32 v104, v104
	v_mfma_f32_32x32x16_bf16 v[16:31], v[6:9], v[208:211], v[16:31]
	v_exp_f32_e32 v105, v105
	v_exp_f32_e32 v106, v106
	v_exp_f32_e32 v107, v107
	v_mfma_f32_32x32x16_bf16 v[62:77], v[2:5], v[236:239], v[62:77]
	v_exp_f32_e32 v108, v108
	v_exp_f32_e32 v109, v109
	v_exp_f32_e32 v110, v110
	v_mfma_f32_32x32x16_bf16 v[62:77], v[6:9], v[236:239], v[62:77]
	v_exp_f32_e32 v111, v111
	v_cvt_pk_bf16_f32 v10, v96, v97
	v_cvt_pk_bf16_f32 v11, v98, v99
	v_cvt_pk_bf16_f32 v12, v100, v101
	v_cvt_pk_bf16_f32 v13, v102, v103
	v_cvt_pk_bf16_f32 v80, v104, v105
	v_cvt_pk_bf16_f32 v81, v106, v107
	v_cvt_pk_bf16_f32 v82, v108, v109
	v_cvt_pk_bf16_f32 v83, v110, v111
	v_mfma_f32_32x32x16_bf16 v[32:47], v[10:13], v[196:199], v[32:47]
	v_mfma_f32_32x32x16_bf16 v[16:31], v[10:13], v[212:215], v[16:31]
	v_mfma_f32_32x32x16_bf16 v[62:77], v[10:13], v[236:239], v[62:77]
	v_mfma_f32_32x32x16_bf16 v[32:47], v[80:83], v[200:203], v[32:47]
	v_mfma_f32_32x32x16_bf16 v[16:31], v[80:83], v[216:219], v[16:31]
	v_mfma_f32_32x32x16_bf16 v[62:77], v[80:83], v[236:239], v[62:77]
.Lfx_skip2:
	s_add_i32 s71, s71, 1
	s_add_i32 s60, s60, 64
	v_subrev_u32_e32 v144, 64, v144
	s_cmp_lt_u32 s71, s41
	s_cbranch_scc1 .Lfx_loop
	s_cmp_eq_u32 s78, 0
	s_cbranch_scc0 .Lfx_done
	s_barrier
.Lfx_done:
	s_nop 7
	s_branch .LBB0_834
